# v023 + FFN1-down and out-proj epilogues: residual loads batched 8 at a time with counted waits, cross-lane sum-of-squares reduction and atomics batched at the end of the tile
# speedup vs baseline: 1.0114x; 1.0027x over previous
; DI float bf_lo(unsigned u) { return __uint_as_float(u << 16); }
; DI float bf_hi(unsigned u) { return __uint_as_float(u & 0xffff0000u); }
;     DI void operator()(Acc& acc, const pg8::Unit& u, int wr, int wc, int fr, int fq, const Pre&) const {
;         const int col = u.pn * 256 + wc * 32 + fq * 8;
; #pragma unroll
;         for (int ai = 0; ai < 2; ++ai)
; #pragma unroll
;             for (int m = 0; m < 4; ++m) {
;                 const int row = u.pm * 256 + ai * 128 + wr * 64 + m * 16 + fr;
;                 float ss = 0.f;
; #pragma unroll
;                 for (int bj = 0; bj < 2; ++bj) {
;                     const size_t off = (size_t)row * DM + col + bj * 128;
;                     f32x4 r0, r1;
;                     if (RES_BF16) { const u32x4 rb = *(const u32x4*)(xb + off); r0 = (f32x4){bf_lo(rb.x), bf_hi(rb.x), bf_lo(rb.y), bf_hi(rb.y)}; r1 = (f32x4){bf_lo(rb.z), bf_hi(rb.z), bf_lo(rb.w), bf_hi(rb.w)}; }
;                     else { r0 = *(const f32x4*)(res + off); r1 = *(const f32x4*)(res + off + 4); }
;                     const f32x4 v0 = r0 + acc[ai][bj][m][0] * coef, v1 = r1 + acc[ai][bj][m][1] * coef;
;                     if (WRITE_F32) { *(f32x4*)(out + off) = v0; *(f32x4*)(out + off + 4) = v1; }
;                     if (WRITE_XB) { store8(xb + off, v0, v1);
;                         ss += (v0[0] * v0[0] + v0[1] * v0[1]) + (v0[2] * v0[2] + v0[3] * v0[3]) + (v1[0] * v1[0] + v1[1] * v1[1]) + (v1[2] * v1[2] + v1[3] * v1[3]); }
;                 }
;                 if (WRITE_XB) { ss += __shfl_xor(ss, 16); ss += __shfl_xor(ss, 32); if (fq == 0) __hip_atomic_fetch_add(ssq + row, ss, __ATOMIC_RELAXED, __HIP_MEMORY_SCOPE_AGENT); }
.LBB0_281:
	v_lshl_add_u32 v224, s58, 8, v147
	v_lshl_or_b32 v158, s59, 8, v153
	v_lshlrev_b32_e32 v159, 11, v224
	v_lshl_add_u32 v158, v158, 1, v159
	v_add_u32_e32 v159, 0x8000, v158
	v_add_u32_e32 v160, 0x10000, v158
	v_add_u32_e32 v161, 0x18000, v158
	v_add_u32_e32 v162, 0x40000, v158
	v_add_u32_e32 v163, 0x48000, v158
	v_add_u32_e32 v164, 0x50000, v158
	v_add_u32_e32 v165, 0x58000, v158
	v_mbcnt_lo_u32_b32 v225, -1, 0
	v_mbcnt_hi_u32_b32 v225, -1, v225
	v_xor_b32_e32 v226, 16, v225
	v_xor_b32_e32 v227, 32, v225
	v_lshlrev_b32_e32 v226, 2, v226
	v_lshlrev_b32_e32 v227, 2, v227
	global_load_dwordx4 v[188:191], v158, s[30:31]
	global_load_dwordx4 v[192:195], v158, s[30:31] offset:256
	global_load_dwordx4 v[196:199], v159, s[30:31]
	global_load_dwordx4 v[200:203], v159, s[30:31] offset:256
	global_load_dwordx4 v[204:207], v160, s[30:31]
	global_load_dwordx4 v[208:211], v160, s[30:31] offset:256
	global_load_dwordx4 v[212:215], v161, s[30:31]
	global_load_dwordx4 v[216:219], v161, s[30:31] offset:256
	s_waitcnt vmcnt(6)
	v_lshlrev_b32_e32 v148, 16, v188
	v_and_b32_e32 v149, 0xffff0000, v188
	v_lshlrev_b32_e32 v182, 16, v189
	v_and_b32_e32 v183, 0xffff0000, v189
	v_lshlrev_b32_e32 v220, 16, v190
	v_and_b32_e32 v221, 0xffff0000, v190
	v_lshlrev_b32_e32 v222, 16, v191
	v_and_b32_e32 v223, 0xffff0000, v191
	v_pk_fma_f32 v[126:127], v[126:127], 0.5, v[148:149] op_sel_hi:[1,0,1]
	v_pk_fma_f32 v[128:129], v[128:129], 0.5, v[182:183] op_sel_hi:[1,0,1]
	v_pk_fma_f32 v[122:123], v[122:123], 0.5, v[220:221] op_sel_hi:[1,0,1]
	v_pk_fma_f32 v[124:125], v[124:125], 0.5, v[222:223] op_sel_hi:[1,0,1]
	v_mul_f32_e32 v166, v126, v126
	v_fmac_f32_e32 v166, v127, v127
	v_fmac_f32_e32 v166, v128, v128
	v_fmac_f32_e32 v166, v129, v129
	v_fmac_f32_e32 v166, v122, v122
	v_fmac_f32_e32 v166, v123, v123
	v_fmac_f32_e32 v166, v124, v124
	v_fmac_f32_e32 v166, v125, v125
	v_cvt_pk_bf16_f32 v188, v126, v127
	v_cvt_pk_bf16_f32 v189, v128, v129
	v_cvt_pk_bf16_f32 v190, v122, v123
	v_cvt_pk_bf16_f32 v191, v124, v125
	global_store_dwordx4 v158, v[188:191], s[30:31]
	v_lshlrev_b32_e32 v148, 16, v192
	v_and_b32_e32 v149, 0xffff0000, v192
	v_lshlrev_b32_e32 v182, 16, v193
	v_and_b32_e32 v183, 0xffff0000, v193
	v_lshlrev_b32_e32 v220, 16, v194
	v_and_b32_e32 v221, 0xffff0000, v194
	v_lshlrev_b32_e32 v222, 16, v195
	v_and_b32_e32 v223, 0xffff0000, v195
	v_pk_fma_f32 v[118:119], v[118:119], 0.5, v[148:149] op_sel_hi:[1,0,1]
	v_pk_fma_f32 v[120:121], v[120:121], 0.5, v[182:183] op_sel_hi:[1,0,1]
	v_pk_fma_f32 v[114:115], v[114:115], 0.5, v[220:221] op_sel_hi:[1,0,1]
	v_pk_fma_f32 v[116:117], v[116:117], 0.5, v[222:223] op_sel_hi:[1,0,1]
	v_fmac_f32_e32 v166, v118, v118
	v_fmac_f32_e32 v166, v119, v119
	v_fmac_f32_e32 v166, v120, v120
	v_fmac_f32_e32 v166, v121, v121
	v_fmac_f32_e32 v166, v114, v114
	v_fmac_f32_e32 v166, v115, v115
	v_fmac_f32_e32 v166, v116, v116
	v_fmac_f32_e32 v166, v117, v117
	v_cvt_pk_bf16_f32 v192, v118, v119
	v_cvt_pk_bf16_f32 v193, v120, v121
	v_cvt_pk_bf16_f32 v194, v114, v115
	v_cvt_pk_bf16_f32 v195, v116, v117
	global_store_dwordx4 v158, v[192:195], s[30:31] offset:256
	s_waitcnt vmcnt(6)
	v_lshlrev_b32_e32 v148, 16, v196
	v_and_b32_e32 v149, 0xffff0000, v196
	v_lshlrev_b32_e32 v182, 16, v197
	v_and_b32_e32 v183, 0xffff0000, v197
	v_lshlrev_b32_e32 v220, 16, v198
	v_and_b32_e32 v221, 0xffff0000, v198
	v_lshlrev_b32_e32 v222, 16, v199
	v_and_b32_e32 v223, 0xffff0000, v199
	v_pk_fma_f32 v[110:111], v[110:111], 0.5, v[148:149] op_sel_hi:[1,0,1]
	v_pk_fma_f32 v[112:113], v[112:113], 0.5, v[182:183] op_sel_hi:[1,0,1]
	v_pk_fma_f32 v[106:107], v[106:107], 0.5, v[220:221] op_sel_hi:[1,0,1]
	v_pk_fma_f32 v[108:109], v[108:109], 0.5, v[222:223] op_sel_hi:[1,0,1]
	v_mul_f32_e32 v167, v110, v110
	v_fmac_f32_e32 v167, v111, v111
	v_fmac_f32_e32 v167, v112, v112
	v_fmac_f32_e32 v167, v113, v113
	v_fmac_f32_e32 v167, v106, v106
	v_fmac_f32_e32 v167, v107, v107
	v_fmac_f32_e32 v167, v108, v108
	v_fmac_f32_e32 v167, v109, v109
	v_cvt_pk_bf16_f32 v196, v110, v111
	v_cvt_pk_bf16_f32 v197, v112, v113
	v_cvt_pk_bf16_f32 v198, v106, v107
	v_cvt_pk_bf16_f32 v199, v108, v109
	global_store_dwordx4 v159, v[196:199], s[30:31]
	v_lshlrev_b32_e32 v148, 16, v200
	v_and_b32_e32 v149, 0xffff0000, v200
	v_lshlrev_b32_e32 v182, 16, v201
	v_and_b32_e32 v183, 0xffff0000, v201
	v_lshlrev_b32_e32 v220, 16, v202
	v_and_b32_e32 v221, 0xffff0000, v202
	v_lshlrev_b32_e32 v222, 16, v203
	v_and_b32_e32 v223, 0xffff0000, v203
	v_pk_fma_f32 v[102:103], v[102:103], 0.5, v[148:149] op_sel_hi:[1,0,1]
	v_pk_fma_f32 v[104:105], v[104:105], 0.5, v[182:183] op_sel_hi:[1,0,1]
	v_pk_fma_f32 v[98:99], v[98:99], 0.5, v[220:221] op_sel_hi:[1,0,1]
	v_pk_fma_f32 v[100:101], v[100:101], 0.5, v[222:223] op_sel_hi:[1,0,1]
	v_fmac_f32_e32 v167, v102, v102
	v_fmac_f32_e32 v167, v103, v103
	v_fmac_f32_e32 v167, v104, v104
	v_fmac_f32_e32 v167, v105, v105
	v_fmac_f32_e32 v167, v98, v98
	v_fmac_f32_e32 v167, v99, v99
	v_fmac_f32_e32 v167, v100, v100
	v_fmac_f32_e32 v167, v101, v101
	v_cvt_pk_bf16_f32 v200, v102, v103
	v_cvt_pk_bf16_f32 v201, v104, v105
	v_cvt_pk_bf16_f32 v202, v98, v99
	v_cvt_pk_bf16_f32 v203, v100, v101
	global_store_dwordx4 v159, v[200:203], s[30:31] offset:256
	s_waitcnt vmcnt(6)
; DI float bf_lo(unsigned u) { return __uint_as_float(u << 16); }
; DI float bf_hi(unsigned u) { return __uint_as_float(u & 0xffff0000u); }
;     DI void operator()(Acc& acc, const pg8::Unit& u, int wr, int wc, int fr, int fq, const Pre&) const {
;     ...
;             for (int m = 0; m < 4; ++m) {
;                 const int row = u.pm * 256 + ai * 128 + wr * 64 + m * 16 + fr;
;                 float ss = 0.f;
; #pragma unroll
;                 for (int bj = 0; bj < 2; ++bj) {
;                     const size_t off = (size_t)row * DM + col + bj * 128;
;                     f32x4 r0, r1;
;                     if (RES_BF16) { const u32x4 rb = *(const u32x4*)(xb + off); r0 = (f32x4){bf_lo(rb.x), bf_hi(rb.x), bf_lo(rb.y), bf_hi(rb.y)}; r1 = (f32x4){bf_lo(rb.z), bf_hi(rb.z), bf_lo(rb.w), bf_hi(rb.w)}; }
;                     else { r0 = *(const f32x4*)(res + off); r1 = *(const f32x4*)(res + off + 4); }
;                     const f32x4 v0 = r0 + acc[ai][bj][m][0] * coef, v1 = r1 + acc[ai][bj][m][1] * coef;
;                     if (WRITE_F32) { *(f32x4*)(out + off) = v0; *(f32x4*)(out + off + 4) = v1; }
;                     if (WRITE_XB) { store8(xb + off, v0, v1);
;                         ss += (v0[0] * v0[0] + v0[1] * v0[1]) + (v0[2] * v0[2] + v0[3] * v0[3]) + (v1[0] * v1[0] + v1[1] * v1[1]) + (v1[2] * v1[2] + v1[3] * v1[3]); }
;                 }
	v_lshlrev_b32_e32 v148, 16, v204
	v_and_b32_e32 v149, 0xffff0000, v204
	v_lshlrev_b32_e32 v182, 16, v205
	v_and_b32_e32 v183, 0xffff0000, v205
	v_lshlrev_b32_e32 v220, 16, v206
	v_and_b32_e32 v221, 0xffff0000, v206
	v_lshlrev_b32_e32 v222, 16, v207
	v_and_b32_e32 v223, 0xffff0000, v207
	v_pk_fma_f32 v[94:95], v[94:95], 0.5, v[148:149] op_sel_hi:[1,0,1]
	v_pk_fma_f32 v[96:97], v[96:97], 0.5, v[182:183] op_sel_hi:[1,0,1]
	v_pk_fma_f32 v[90:91], v[90:91], 0.5, v[220:221] op_sel_hi:[1,0,1]
	v_pk_fma_f32 v[92:93], v[92:93], 0.5, v[222:223] op_sel_hi:[1,0,1]
	v_mul_f32_e32 v168, v94, v94
	v_fmac_f32_e32 v168, v95, v95
	v_fmac_f32_e32 v168, v96, v96
	v_fmac_f32_e32 v168, v97, v97
	v_fmac_f32_e32 v168, v90, v90
	v_fmac_f32_e32 v168, v91, v91
	v_fmac_f32_e32 v168, v92, v92
	v_fmac_f32_e32 v168, v93, v93
	v_cvt_pk_bf16_f32 v204, v94, v95
	v_cvt_pk_bf16_f32 v205, v96, v97
	v_cvt_pk_bf16_f32 v206, v90, v91
	v_cvt_pk_bf16_f32 v207, v92, v93
	global_store_dwordx4 v160, v[204:207], s[30:31]
	v_lshlrev_b32_e32 v148, 16, v208
	v_and_b32_e32 v149, 0xffff0000, v208
	v_lshlrev_b32_e32 v182, 16, v209
	v_and_b32_e32 v183, 0xffff0000, v209
	v_lshlrev_b32_e32 v220, 16, v210
	v_and_b32_e32 v221, 0xffff0000, v210
	v_lshlrev_b32_e32 v222, 16, v211
	v_and_b32_e32 v223, 0xffff0000, v211
	v_pk_fma_f32 v[86:87], v[86:87], 0.5, v[148:149] op_sel_hi:[1,0,1]
	v_pk_fma_f32 v[88:89], v[88:89], 0.5, v[182:183] op_sel_hi:[1,0,1]
	v_pk_fma_f32 v[82:83], v[82:83], 0.5, v[220:221] op_sel_hi:[1,0,1]
	v_pk_fma_f32 v[84:85], v[84:85], 0.5, v[222:223] op_sel_hi:[1,0,1]
	v_fmac_f32_e32 v168, v86, v86
	v_fmac_f32_e32 v168, v87, v87
	v_fmac_f32_e32 v168, v88, v88
	v_fmac_f32_e32 v168, v89, v89
	v_fmac_f32_e32 v168, v82, v82
	v_fmac_f32_e32 v168, v83, v83
	v_fmac_f32_e32 v168, v84, v84
	v_fmac_f32_e32 v168, v85, v85
	v_cvt_pk_bf16_f32 v208, v86, v87
	v_cvt_pk_bf16_f32 v209, v88, v89
	v_cvt_pk_bf16_f32 v210, v82, v83
	v_cvt_pk_bf16_f32 v211, v84, v85
	global_store_dwordx4 v160, v[208:211], s[30:31] offset:256
	s_waitcnt vmcnt(6)
	v_lshlrev_b32_e32 v148, 16, v212
	v_and_b32_e32 v149, 0xffff0000, v212
	v_lshlrev_b32_e32 v182, 16, v213
	v_and_b32_e32 v183, 0xffff0000, v213
	v_lshlrev_b32_e32 v220, 16, v214
	v_and_b32_e32 v221, 0xffff0000, v214
	v_lshlrev_b32_e32 v222, 16, v215
	v_and_b32_e32 v223, 0xffff0000, v215
	v_pk_fma_f32 v[78:79], v[78:79], 0.5, v[148:149] op_sel_hi:[1,0,1]
	v_pk_fma_f32 v[80:81], v[80:81], 0.5, v[182:183] op_sel_hi:[1,0,1]
	v_pk_fma_f32 v[74:75], v[74:75], 0.5, v[220:221] op_sel_hi:[1,0,1]
	v_pk_fma_f32 v[76:77], v[76:77], 0.5, v[222:223] op_sel_hi:[1,0,1]
	v_mul_f32_e32 v169, v78, v78
	v_fmac_f32_e32 v169, v79, v79
	v_fmac_f32_e32 v169, v80, v80
	v_fmac_f32_e32 v169, v81, v81
	v_fmac_f32_e32 v169, v74, v74
	v_fmac_f32_e32 v169, v75, v75
	v_fmac_f32_e32 v169, v76, v76
	v_fmac_f32_e32 v169, v77, v77
	v_cvt_pk_bf16_f32 v212, v78, v79
	v_cvt_pk_bf16_f32 v213, v80, v81
	v_cvt_pk_bf16_f32 v214, v74, v75
	v_cvt_pk_bf16_f32 v215, v76, v77
	global_store_dwordx4 v161, v[212:215], s[30:31]
	v_lshlrev_b32_e32 v148, 16, v216
	v_and_b32_e32 v149, 0xffff0000, v216
	v_lshlrev_b32_e32 v182, 16, v217
	v_and_b32_e32 v183, 0xffff0000, v217
	v_lshlrev_b32_e32 v220, 16, v218
	v_and_b32_e32 v221, 0xffff0000, v218
	v_lshlrev_b32_e32 v222, 16, v219
	v_and_b32_e32 v223, 0xffff0000, v219
	v_pk_fma_f32 v[70:71], v[70:71], 0.5, v[148:149] op_sel_hi:[1,0,1]
	v_pk_fma_f32 v[72:73], v[72:73], 0.5, v[182:183] op_sel_hi:[1,0,1]
	v_pk_fma_f32 v[66:67], v[66:67], 0.5, v[220:221] op_sel_hi:[1,0,1]
	v_pk_fma_f32 v[68:69], v[68:69], 0.5, v[222:223] op_sel_hi:[1,0,1]
	v_fmac_f32_e32 v169, v70, v70
	v_fmac_f32_e32 v169, v71, v71
	v_fmac_f32_e32 v169, v72, v72
	v_fmac_f32_e32 v169, v73, v73
	v_fmac_f32_e32 v169, v66, v66
	v_fmac_f32_e32 v169, v67, v67
	v_fmac_f32_e32 v169, v68, v68
	v_fmac_f32_e32 v169, v69, v69
	v_cvt_pk_bf16_f32 v216, v70, v71
	v_cvt_pk_bf16_f32 v217, v72, v73
	v_cvt_pk_bf16_f32 v218, v66, v67
	v_cvt_pk_bf16_f32 v219, v68, v69
	global_store_dwordx4 v161, v[216:219], s[30:31] offset:256
	global_load_dwordx4 v[188:191], v162, s[30:31]
	global_load_dwordx4 v[192:195], v162, s[30:31] offset:256
	global_load_dwordx4 v[196:199], v163, s[30:31]
	global_load_dwordx4 v[200:203], v163, s[30:31] offset:256
	global_load_dwordx4 v[204:207], v164, s[30:31]
	global_load_dwordx4 v[208:211], v164, s[30:31] offset:256
	global_load_dwordx4 v[212:215], v165, s[30:31]
	global_load_dwordx4 v[216:219], v165, s[30:31] offset:256
	s_waitcnt vmcnt(6)
	v_lshlrev_b32_e32 v148, 16, v188
	v_and_b32_e32 v149, 0xffff0000, v188
	v_lshlrev_b32_e32 v182, 16, v189
	v_and_b32_e32 v183, 0xffff0000, v189
	v_lshlrev_b32_e32 v220, 16, v190
	v_and_b32_e32 v221, 0xffff0000, v190
	v_lshlrev_b32_e32 v222, 16, v191
	v_and_b32_e32 v223, 0xffff0000, v191
	v_pk_fma_f32 v[62:63], v[62:63], 0.5, v[148:149] op_sel_hi:[1,0,1]
	v_pk_fma_f32 v[64:65], v[64:65], 0.5, v[182:183] op_sel_hi:[1,0,1]
	v_pk_fma_f32 v[58:59], v[58:59], 0.5, v[220:221] op_sel_hi:[1,0,1]
	v_pk_fma_f32 v[60:61], v[60:61], 0.5, v[222:223] op_sel_hi:[1,0,1]
	v_mul_f32_e32 v170, v62, v62
	v_fmac_f32_e32 v170, v63, v63
	v_fmac_f32_e32 v170, v64, v64
	v_fmac_f32_e32 v170, v65, v65
	v_fmac_f32_e32 v170, v58, v58
	v_fmac_f32_e32 v170, v59, v59
	v_fmac_f32_e32 v170, v60, v60
	v_fmac_f32_e32 v170, v61, v61
	v_cvt_pk_bf16_f32 v188, v62, v63
	v_cvt_pk_bf16_f32 v189, v64, v65
	v_cvt_pk_bf16_f32 v190, v58, v59
	v_cvt_pk_bf16_f32 v191, v60, v61
	global_store_dwordx4 v162, v[188:191], s[30:31]
	v_lshlrev_b32_e32 v148, 16, v192
	v_and_b32_e32 v149, 0xffff0000, v192
	v_lshlrev_b32_e32 v182, 16, v193
	v_and_b32_e32 v183, 0xffff0000, v193
	v_lshlrev_b32_e32 v220, 16, v194
	v_and_b32_e32 v221, 0xffff0000, v194
	v_lshlrev_b32_e32 v222, 16, v195
	v_and_b32_e32 v223, 0xffff0000, v195
	v_pk_fma_f32 v[54:55], v[54:55], 0.5, v[148:149] op_sel_hi:[1,0,1]
	v_pk_fma_f32 v[56:57], v[56:57], 0.5, v[182:183] op_sel_hi:[1,0,1]
	v_pk_fma_f32 v[50:51], v[50:51], 0.5, v[220:221] op_sel_hi:[1,0,1]
	v_pk_fma_f32 v[52:53], v[52:53], 0.5, v[222:223] op_sel_hi:[1,0,1]
	v_fmac_f32_e32 v170, v54, v54
	v_fmac_f32_e32 v170, v55, v55
	v_fmac_f32_e32 v170, v56, v56
	v_fmac_f32_e32 v170, v57, v57
	v_fmac_f32_e32 v170, v50, v50
	v_fmac_f32_e32 v170, v51, v51
	v_fmac_f32_e32 v170, v52, v52
	v_fmac_f32_e32 v170, v53, v53
	v_cvt_pk_bf16_f32 v192, v54, v55
	v_cvt_pk_bf16_f32 v193, v56, v57
	v_cvt_pk_bf16_f32 v194, v50, v51
	v_cvt_pk_bf16_f32 v195, v52, v53
	global_store_dwordx4 v162, v[192:195], s[30:31] offset:256
	s_waitcnt vmcnt(6)
; DI float bf_lo(unsigned u) { return __uint_as_float(u << 16); }
; DI float bf_hi(unsigned u) { return __uint_as_float(u & 0xffff0000u); }
;     DI void operator()(Acc& acc, const pg8::Unit& u, int wr, int wc, int fr, int fq, const Pre&) const {
;     ...
;             for (int m = 0; m < 4; ++m) {
;                 const int row = u.pm * 256 + ai * 128 + wr * 64 + m * 16 + fr;
;                 float ss = 0.f;
; #pragma unroll
;                 for (int bj = 0; bj < 2; ++bj) {
;                     const size_t off = (size_t)row * DM + col + bj * 128;
;                     f32x4 r0, r1;
;                     if (RES_BF16) { const u32x4 rb = *(const u32x4*)(xb + off); r0 = (f32x4){bf_lo(rb.x), bf_hi(rb.x), bf_lo(rb.y), bf_hi(rb.y)}; r1 = (f32x4){bf_lo(rb.z), bf_hi(rb.z), bf_lo(rb.w), bf_hi(rb.w)}; }
;                     else { r0 = *(const f32x4*)(res + off); r1 = *(const f32x4*)(res + off + 4); }
;                     const f32x4 v0 = r0 + acc[ai][bj][m][0] * coef, v1 = r1 + acc[ai][bj][m][1] * coef;
;                     if (WRITE_F32) { *(f32x4*)(out + off) = v0; *(f32x4*)(out + off + 4) = v1; }
;                     if (WRITE_XB) { store8(xb + off, v0, v1);
;                         ss += (v0[0] * v0[0] + v0[1] * v0[1]) + (v0[2] * v0[2] + v0[3] * v0[3]) + (v1[0] * v1[0] + v1[1] * v1[1]) + (v1[2] * v1[2] + v1[3] * v1[3]); }
;                 }
	v_lshlrev_b32_e32 v148, 16, v196
	v_and_b32_e32 v149, 0xffff0000, v196
	v_lshlrev_b32_e32 v182, 16, v197
	v_and_b32_e32 v183, 0xffff0000, v197
	v_lshlrev_b32_e32 v220, 16, v198
	v_and_b32_e32 v221, 0xffff0000, v198
	v_lshlrev_b32_e32 v222, 16, v199
	v_and_b32_e32 v223, 0xffff0000, v199
	v_pk_fma_f32 v[46:47], v[46:47], 0.5, v[148:149] op_sel_hi:[1,0,1]
	v_pk_fma_f32 v[48:49], v[48:49], 0.5, v[182:183] op_sel_hi:[1,0,1]
	v_pk_fma_f32 v[42:43], v[42:43], 0.5, v[220:221] op_sel_hi:[1,0,1]
	v_pk_fma_f32 v[44:45], v[44:45], 0.5, v[222:223] op_sel_hi:[1,0,1]
	v_mul_f32_e32 v171, v46, v46
	v_fmac_f32_e32 v171, v47, v47
	v_fmac_f32_e32 v171, v48, v48
	v_fmac_f32_e32 v171, v49, v49
	v_fmac_f32_e32 v171, v42, v42
	v_fmac_f32_e32 v171, v43, v43
	v_fmac_f32_e32 v171, v44, v44
	v_fmac_f32_e32 v171, v45, v45
	v_cvt_pk_bf16_f32 v196, v46, v47
	v_cvt_pk_bf16_f32 v197, v48, v49
	v_cvt_pk_bf16_f32 v198, v42, v43
	v_cvt_pk_bf16_f32 v199, v44, v45
	global_store_dwordx4 v163, v[196:199], s[30:31]
	v_lshlrev_b32_e32 v148, 16, v200
	v_and_b32_e32 v149, 0xffff0000, v200
	v_lshlrev_b32_e32 v182, 16, v201
	v_and_b32_e32 v183, 0xffff0000, v201
	v_lshlrev_b32_e32 v220, 16, v202
	v_and_b32_e32 v221, 0xffff0000, v202
	v_lshlrev_b32_e32 v222, 16, v203
	v_and_b32_e32 v223, 0xffff0000, v203
	v_pk_fma_f32 v[38:39], v[38:39], 0.5, v[148:149] op_sel_hi:[1,0,1]
	v_pk_fma_f32 v[40:41], v[40:41], 0.5, v[182:183] op_sel_hi:[1,0,1]
	v_pk_fma_f32 v[34:35], v[34:35], 0.5, v[220:221] op_sel_hi:[1,0,1]
	v_pk_fma_f32 v[36:37], v[36:37], 0.5, v[222:223] op_sel_hi:[1,0,1]
	v_fmac_f32_e32 v171, v38, v38
	v_fmac_f32_e32 v171, v39, v39
	v_fmac_f32_e32 v171, v40, v40
	v_fmac_f32_e32 v171, v41, v41
	v_fmac_f32_e32 v171, v34, v34
	v_fmac_f32_e32 v171, v35, v35
	v_fmac_f32_e32 v171, v36, v36
	v_fmac_f32_e32 v171, v37, v37
	v_cvt_pk_bf16_f32 v200, v38, v39
	v_cvt_pk_bf16_f32 v201, v40, v41
	v_cvt_pk_bf16_f32 v202, v34, v35
	v_cvt_pk_bf16_f32 v203, v36, v37
	global_store_dwordx4 v163, v[200:203], s[30:31] offset:256
	s_waitcnt vmcnt(6)
	v_lshlrev_b32_e32 v148, 16, v204
	v_and_b32_e32 v149, 0xffff0000, v204
	v_lshlrev_b32_e32 v182, 16, v205
	v_and_b32_e32 v183, 0xffff0000, v205
	v_lshlrev_b32_e32 v220, 16, v206
	v_and_b32_e32 v221, 0xffff0000, v206
	v_lshlrev_b32_e32 v222, 16, v207
	v_and_b32_e32 v223, 0xffff0000, v207
	v_pk_fma_f32 v[30:31], v[30:31], 0.5, v[148:149] op_sel_hi:[1,0,1]
	v_pk_fma_f32 v[32:33], v[32:33], 0.5, v[182:183] op_sel_hi:[1,0,1]
	v_pk_fma_f32 v[26:27], v[26:27], 0.5, v[220:221] op_sel_hi:[1,0,1]
	v_pk_fma_f32 v[28:29], v[28:29], 0.5, v[222:223] op_sel_hi:[1,0,1]
	v_mul_f32_e32 v172, v30, v30
	v_fmac_f32_e32 v172, v31, v31
	v_fmac_f32_e32 v172, v32, v32
	v_fmac_f32_e32 v172, v33, v33
	v_fmac_f32_e32 v172, v26, v26
	v_fmac_f32_e32 v172, v27, v27
	v_fmac_f32_e32 v172, v28, v28
	v_fmac_f32_e32 v172, v29, v29
	v_cvt_pk_bf16_f32 v204, v30, v31
	v_cvt_pk_bf16_f32 v205, v32, v33
	v_cvt_pk_bf16_f32 v206, v26, v27
	v_cvt_pk_bf16_f32 v207, v28, v29
	global_store_dwordx4 v164, v[204:207], s[30:31]
	v_lshlrev_b32_e32 v148, 16, v208
	v_and_b32_e32 v149, 0xffff0000, v208
	v_lshlrev_b32_e32 v182, 16, v209
	v_and_b32_e32 v183, 0xffff0000, v209
	v_lshlrev_b32_e32 v220, 16, v210
	v_and_b32_e32 v221, 0xffff0000, v210
	v_lshlrev_b32_e32 v222, 16, v211
	v_and_b32_e32 v223, 0xffff0000, v211
	v_pk_fma_f32 v[22:23], v[22:23], 0.5, v[148:149] op_sel_hi:[1,0,1]
	v_pk_fma_f32 v[24:25], v[24:25], 0.5, v[182:183] op_sel_hi:[1,0,1]
	v_pk_fma_f32 v[18:19], v[18:19], 0.5, v[220:221] op_sel_hi:[1,0,1]
	v_pk_fma_f32 v[20:21], v[20:21], 0.5, v[222:223] op_sel_hi:[1,0,1]
	v_fmac_f32_e32 v172, v22, v22
	v_fmac_f32_e32 v172, v23, v23
	v_fmac_f32_e32 v172, v24, v24
	v_fmac_f32_e32 v172, v25, v25
	v_fmac_f32_e32 v172, v18, v18
	v_fmac_f32_e32 v172, v19, v19
	v_fmac_f32_e32 v172, v20, v20
	v_fmac_f32_e32 v172, v21, v21
	v_cvt_pk_bf16_f32 v208, v22, v23
	v_cvt_pk_bf16_f32 v209, v24, v25
	v_cvt_pk_bf16_f32 v210, v18, v19
	v_cvt_pk_bf16_f32 v211, v20, v21
	global_store_dwordx4 v164, v[208:211], s[30:31] offset:256
	s_waitcnt vmcnt(6)
;     DI void operator()(Acc& acc, const pg8::Unit& u, int wr, int wc, int fr, int fq, const Pre&) const {
;     ...
;                     if (WRITE_XB) { store8(xb + off, v0, v1);
;                         ss += (v0[0] * v0[0] + v0[1] * v0[1]) + (v0[2] * v0[2] + v0[3] * v0[3]) + (v1[0] * v1[0] + v1[1] * v1[1]) + (v1[2] * v1[2] + v1[3] * v1[3]); }
;                 }
;                 if (WRITE_XB) { ss += __shfl_xor(ss, 16); ss += __shfl_xor(ss, 32); if (fq == 0) __hip_atomic_fetch_add(ssq + row, ss, __ATOMIC_RELAXED, __HIP_MEMORY_SCOPE_AGENT); }
	v_lshlrev_b32_e32 v148, 16, v212
	v_and_b32_e32 v149, 0xffff0000, v212
	v_lshlrev_b32_e32 v182, 16, v213
	v_and_b32_e32 v183, 0xffff0000, v213
	v_lshlrev_b32_e32 v220, 16, v214
	v_and_b32_e32 v221, 0xffff0000, v214
	v_lshlrev_b32_e32 v222, 16, v215
	v_and_b32_e32 v223, 0xffff0000, v215
	v_pk_fma_f32 v[14:15], v[14:15], 0.5, v[148:149] op_sel_hi:[1,0,1]
	v_pk_fma_f32 v[16:17], v[16:17], 0.5, v[182:183] op_sel_hi:[1,0,1]
	v_pk_fma_f32 v[10:11], v[10:11], 0.5, v[220:221] op_sel_hi:[1,0,1]
	v_pk_fma_f32 v[12:13], v[12:13], 0.5, v[222:223] op_sel_hi:[1,0,1]
	v_mul_f32_e32 v173, v14, v14
	v_fmac_f32_e32 v173, v15, v15
	v_fmac_f32_e32 v173, v16, v16
	v_fmac_f32_e32 v173, v17, v17
	v_fmac_f32_e32 v173, v10, v10
	v_fmac_f32_e32 v173, v11, v11
	v_fmac_f32_e32 v173, v12, v12
	v_fmac_f32_e32 v173, v13, v13
	v_cvt_pk_bf16_f32 v212, v14, v15
	v_cvt_pk_bf16_f32 v213, v16, v17
	v_cvt_pk_bf16_f32 v214, v10, v11
	v_cvt_pk_bf16_f32 v215, v12, v13
	global_store_dwordx4 v165, v[212:215], s[30:31]
	v_lshlrev_b32_e32 v148, 16, v216
	v_and_b32_e32 v149, 0xffff0000, v216
	v_lshlrev_b32_e32 v182, 16, v217
	v_and_b32_e32 v183, 0xffff0000, v217
	v_lshlrev_b32_e32 v220, 16, v218
	v_and_b32_e32 v221, 0xffff0000, v218
	v_lshlrev_b32_e32 v222, 16, v219
	v_and_b32_e32 v223, 0xffff0000, v219
	v_pk_fma_f32 v[6:7], v[6:7], 0.5, v[148:149] op_sel_hi:[1,0,1]
	v_pk_fma_f32 v[8:9], v[8:9], 0.5, v[182:183] op_sel_hi:[1,0,1]
	v_pk_fma_f32 v[2:3], v[2:3], 0.5, v[220:221] op_sel_hi:[1,0,1]
	v_pk_fma_f32 v[4:5], v[4:5], 0.5, v[222:223] op_sel_hi:[1,0,1]
	v_fmac_f32_e32 v173, v6, v6
	v_fmac_f32_e32 v173, v7, v7
	v_fmac_f32_e32 v173, v8, v8
	v_fmac_f32_e32 v173, v9, v9
	v_fmac_f32_e32 v173, v2, v2
	v_fmac_f32_e32 v173, v3, v3
	v_fmac_f32_e32 v173, v4, v4
	v_fmac_f32_e32 v173, v5, v5
	v_cvt_pk_bf16_f32 v216, v6, v7
	v_cvt_pk_bf16_f32 v217, v8, v9
	v_cvt_pk_bf16_f32 v218, v2, v3
	v_cvt_pk_bf16_f32 v219, v4, v5
	global_store_dwordx4 v165, v[216:219], s[30:31] offset:256
	ds_bpermute_b32 v174, v226, v166
	ds_bpermute_b32 v175, v226, v167
	ds_bpermute_b32 v176, v226, v168
	ds_bpermute_b32 v177, v226, v169
	ds_bpermute_b32 v178, v226, v170
	ds_bpermute_b32 v179, v226, v171
	ds_bpermute_b32 v180, v226, v172
	ds_bpermute_b32 v181, v226, v173
	s_waitcnt lgkmcnt(0)
	v_add_f32_e32 v166, v166, v174
	v_add_f32_e32 v167, v167, v175
	v_add_f32_e32 v168, v168, v176
	v_add_f32_e32 v169, v169, v177
	v_add_f32_e32 v170, v170, v178
	v_add_f32_e32 v171, v171, v179
	v_add_f32_e32 v172, v172, v180
	v_add_f32_e32 v173, v173, v181
	ds_bpermute_b32 v174, v227, v166
	ds_bpermute_b32 v175, v227, v167
	ds_bpermute_b32 v176, v227, v168
	ds_bpermute_b32 v177, v227, v169
	ds_bpermute_b32 v178, v227, v170
	ds_bpermute_b32 v179, v227, v171
	ds_bpermute_b32 v180, v227, v172
	ds_bpermute_b32 v181, v227, v173
	s_waitcnt lgkmcnt(0)
	v_add_f32_e32 v166, v166, v174
	v_add_f32_e32 v167, v167, v175
	v_add_f32_e32 v168, v168, v176
	v_add_f32_e32 v169, v169, v177
	v_add_f32_e32 v170, v170, v178
	v_add_f32_e32 v171, v171, v179
	v_add_f32_e32 v172, v172, v180
	v_add_f32_e32 v173, v173, v181
	v_lshlrev_b32_e32 v224, 2, v224
	s_and_saveexec_b64 s[36:37], s[4:5]
	global_atomic_add_f32 v224, v166, s[20:21]
	global_atomic_add_f32 v224, v167, s[20:21] offset:64
	global_atomic_add_f32 v224, v168, s[20:21] offset:128
	global_atomic_add_f32 v224, v169, s[20:21] offset:192
	global_atomic_add_f32 v224, v170, s[20:21] offset:512
	global_atomic_add_f32 v224, v171, s[20:21] offset:576
	global_atomic_add_f32 v224, v172, s[20:21] offset:640
	global_atomic_add_f32 v224, v173, s[20:21] offset:704

; DI float bf_lo(unsigned u) { return __uint_as_float(u << 16); }
; DI float bf_hi(unsigned u) { return __uint_as_float(u & 0xffff0000u); }
;     DI void operator()(Acc& acc, const pg8::Unit& u, int wr, int wc, int fr, int fq, const Pre&) const {
;         const int col = u.pn * 256 + wc * 32 + fq * 8;
; #pragma unroll
;         for (int ai = 0; ai < 2; ++ai)
; #pragma unroll
;             for (int m = 0; m < 4; ++m) {
;                 const int row = u.pm * 256 + ai * 128 + wr * 64 + m * 16 + fr;
;                 float ss = 0.f;
; #pragma unroll
;                 for (int bj = 0; bj < 2; ++bj) {
;                     const size_t off = (size_t)row * DM + col + bj * 128;
;                     f32x4 r0, r1;
;                     if (RES_BF16) { const u32x4 rb = *(const u32x4*)(xb + off); r0 = (f32x4){bf_lo(rb.x), bf_hi(rb.x), bf_lo(rb.y), bf_hi(rb.y)}; r1 = (f32x4){bf_lo(rb.z), bf_hi(rb.z), bf_lo(rb.w), bf_hi(rb.w)}; }
;                     else { r0 = *(const f32x4*)(res + off); r1 = *(const f32x4*)(res + off + 4); }
;                     const f32x4 v0 = r0 + acc[ai][bj][m][0] * coef, v1 = r1 + acc[ai][bj][m][1] * coef;
;                     if (WRITE_F32) { *(f32x4*)(out + off) = v0; *(f32x4*)(out + off + 4) = v1; }
;                     if (WRITE_XB) { store8(xb + off, v0, v1);
;                         ss += (v0[0] * v0[0] + v0[1] * v0[1]) + (v0[2] * v0[2] + v0[3] * v0[3]) + (v1[0] * v1[0] + v1[1] * v1[1]) + (v1[2] * v1[2] + v1[3] * v1[3]); }
;                 }
;                 if (WRITE_XB) { ss += __shfl_xor(ss, 16); ss += __shfl_xor(ss, 32); if (fq == 0) __hip_atomic_fetch_add(ssq + row, ss, __ATOMIC_RELAXED, __HIP_MEMORY_SCOPE_AGENT); }
.LBB0_1136:
	v_lshl_add_u32 v224, s40, 8, v1
	v_lshl_or_b32 v158, s42, 8, v151
	v_lshlrev_b32_e32 v159, 11, v224
	v_lshl_add_u32 v158, v158, 1, v159
	v_add_u32_e32 v159, 0x8000, v158
	v_add_u32_e32 v160, 0x10000, v158
	v_add_u32_e32 v161, 0x18000, v158
	v_add_u32_e32 v162, 0x40000, v158
	v_add_u32_e32 v163, 0x48000, v158
	v_add_u32_e32 v164, 0x50000, v158
	v_add_u32_e32 v165, 0x58000, v158
	v_mbcnt_lo_u32_b32 v225, -1, 0
	v_mbcnt_hi_u32_b32 v225, -1, v225
	v_xor_b32_e32 v226, 16, v225
	v_xor_b32_e32 v227, 32, v225
	v_lshlrev_b32_e32 v226, 2, v226
	v_lshlrev_b32_e32 v227, 2, v227
	global_load_dwordx4 v[188:191], v158, s[30:31]
	global_load_dwordx4 v[192:195], v158, s[30:31] offset:256
	global_load_dwordx4 v[196:199], v159, s[30:31]
	global_load_dwordx4 v[200:203], v159, s[30:31] offset:256
	global_load_dwordx4 v[204:207], v160, s[30:31]
	global_load_dwordx4 v[208:211], v160, s[30:31] offset:256
	global_load_dwordx4 v[212:215], v161, s[30:31]
	global_load_dwordx4 v[216:219], v161, s[30:31] offset:256
	s_waitcnt vmcnt(6)
	v_lshlrev_b32_e32 v148, 16, v188
	v_and_b32_e32 v149, 0xffff0000, v188
	v_lshlrev_b32_e32 v182, 16, v189
	v_and_b32_e32 v183, 0xffff0000, v189
	v_lshlrev_b32_e32 v220, 16, v190
	v_and_b32_e32 v221, 0xffff0000, v190
	v_lshlrev_b32_e32 v222, 16, v191
	v_and_b32_e32 v223, 0xffff0000, v191
	v_pk_add_f32 v[126:127], v[126:127], v[148:149]
	v_pk_add_f32 v[128:129], v[128:129], v[182:183]
	v_pk_add_f32 v[122:123], v[122:123], v[220:221]
	v_pk_add_f32 v[124:125], v[124:125], v[222:223]
	v_mul_f32_e32 v166, v126, v126
	v_fmac_f32_e32 v166, v127, v127
	v_fmac_f32_e32 v166, v128, v128
	v_fmac_f32_e32 v166, v129, v129
	v_fmac_f32_e32 v166, v122, v122
	v_fmac_f32_e32 v166, v123, v123
	v_fmac_f32_e32 v166, v124, v124
	v_fmac_f32_e32 v166, v125, v125
	v_cvt_pk_bf16_f32 v188, v126, v127
	v_cvt_pk_bf16_f32 v189, v128, v129
	v_cvt_pk_bf16_f32 v190, v122, v123
	v_cvt_pk_bf16_f32 v191, v124, v125
	global_store_dwordx4 v158, v[188:191], s[30:31]
	v_lshlrev_b32_e32 v148, 16, v192
	v_and_b32_e32 v149, 0xffff0000, v192
	v_lshlrev_b32_e32 v182, 16, v193
	v_and_b32_e32 v183, 0xffff0000, v193
	v_lshlrev_b32_e32 v220, 16, v194
	v_and_b32_e32 v221, 0xffff0000, v194
	v_lshlrev_b32_e32 v222, 16, v195
	v_and_b32_e32 v223, 0xffff0000, v195
	v_pk_add_f32 v[118:119], v[118:119], v[148:149]
	v_pk_add_f32 v[120:121], v[120:121], v[182:183]
	v_pk_add_f32 v[114:115], v[114:115], v[220:221]
	v_pk_add_f32 v[116:117], v[116:117], v[222:223]
	v_fmac_f32_e32 v166, v118, v118
	v_fmac_f32_e32 v166, v119, v119
	v_fmac_f32_e32 v166, v120, v120
	v_fmac_f32_e32 v166, v121, v121
	v_fmac_f32_e32 v166, v114, v114
	v_fmac_f32_e32 v166, v115, v115
	v_fmac_f32_e32 v166, v116, v116
	v_fmac_f32_e32 v166, v117, v117
	v_cvt_pk_bf16_f32 v192, v118, v119
	v_cvt_pk_bf16_f32 v193, v120, v121
	v_cvt_pk_bf16_f32 v194, v114, v115
	v_cvt_pk_bf16_f32 v195, v116, v117
	global_store_dwordx4 v158, v[192:195], s[30:31] offset:256
	s_waitcnt vmcnt(6)
	v_lshlrev_b32_e32 v148, 16, v196
	v_and_b32_e32 v149, 0xffff0000, v196
	v_lshlrev_b32_e32 v182, 16, v197
	v_and_b32_e32 v183, 0xffff0000, v197
	v_lshlrev_b32_e32 v220, 16, v198
	v_and_b32_e32 v221, 0xffff0000, v198
	v_lshlrev_b32_e32 v222, 16, v199
	v_and_b32_e32 v223, 0xffff0000, v199
	v_pk_add_f32 v[110:111], v[110:111], v[148:149]
	v_pk_add_f32 v[112:113], v[112:113], v[182:183]
	v_pk_add_f32 v[106:107], v[106:107], v[220:221]
	v_pk_add_f32 v[108:109], v[108:109], v[222:223]
	v_mul_f32_e32 v167, v110, v110
	v_fmac_f32_e32 v167, v111, v111
	v_fmac_f32_e32 v167, v112, v112
	v_fmac_f32_e32 v167, v113, v113
	v_fmac_f32_e32 v167, v106, v106
	v_fmac_f32_e32 v167, v107, v107
	v_fmac_f32_e32 v167, v108, v108
	v_fmac_f32_e32 v167, v109, v109
	v_cvt_pk_bf16_f32 v196, v110, v111
	v_cvt_pk_bf16_f32 v197, v112, v113
	v_cvt_pk_bf16_f32 v198, v106, v107
	v_cvt_pk_bf16_f32 v199, v108, v109
	global_store_dwordx4 v159, v[196:199], s[30:31]
	v_lshlrev_b32_e32 v148, 16, v200
	v_and_b32_e32 v149, 0xffff0000, v200
	v_lshlrev_b32_e32 v182, 16, v201
	v_and_b32_e32 v183, 0xffff0000, v201
	v_lshlrev_b32_e32 v220, 16, v202
	v_and_b32_e32 v221, 0xffff0000, v202
	v_lshlrev_b32_e32 v222, 16, v203
	v_and_b32_e32 v223, 0xffff0000, v203
	v_pk_add_f32 v[102:103], v[102:103], v[148:149]
	v_pk_add_f32 v[104:105], v[104:105], v[182:183]
	v_pk_add_f32 v[98:99], v[98:99], v[220:221]
	v_pk_add_f32 v[100:101], v[100:101], v[222:223]
	v_fmac_f32_e32 v167, v102, v102
	v_fmac_f32_e32 v167, v103, v103
	v_fmac_f32_e32 v167, v104, v104
	v_fmac_f32_e32 v167, v105, v105
	v_fmac_f32_e32 v167, v98, v98
	v_fmac_f32_e32 v167, v99, v99
	v_fmac_f32_e32 v167, v100, v100
	v_fmac_f32_e32 v167, v101, v101
	v_cvt_pk_bf16_f32 v200, v102, v103
	v_cvt_pk_bf16_f32 v201, v104, v105
	v_cvt_pk_bf16_f32 v202, v98, v99
	v_cvt_pk_bf16_f32 v203, v100, v101
	global_store_dwordx4 v159, v[200:203], s[30:31] offset:256
	s_waitcnt vmcnt(6)
; DI float bf_lo(unsigned u) { return __uint_as_float(u << 16); }
; DI float bf_hi(unsigned u) { return __uint_as_float(u & 0xffff0000u); }
;     DI void operator()(Acc& acc, const pg8::Unit& u, int wr, int wc, int fr, int fq, const Pre&) const {
;     ...
;             for (int m = 0; m < 4; ++m) {
;                 const int row = u.pm * 256 + ai * 128 + wr * 64 + m * 16 + fr;
;                 float ss = 0.f;
; #pragma unroll
;                 for (int bj = 0; bj < 2; ++bj) {
;                     const size_t off = (size_t)row * DM + col + bj * 128;
;                     f32x4 r0, r1;
;                     if (RES_BF16) { const u32x4 rb = *(const u32x4*)(xb + off); r0 = (f32x4){bf_lo(rb.x), bf_hi(rb.x), bf_lo(rb.y), bf_hi(rb.y)}; r1 = (f32x4){bf_lo(rb.z), bf_hi(rb.z), bf_lo(rb.w), bf_hi(rb.w)}; }
;                     else { r0 = *(const f32x4*)(res + off); r1 = *(const f32x4*)(res + off + 4); }
;                     const f32x4 v0 = r0 + acc[ai][bj][m][0] * coef, v1 = r1 + acc[ai][bj][m][1] * coef;
;                     if (WRITE_F32) { *(f32x4*)(out + off) = v0; *(f32x4*)(out + off + 4) = v1; }
;                     if (WRITE_XB) { store8(xb + off, v0, v1);
;                         ss += (v0[0] * v0[0] + v0[1] * v0[1]) + (v0[2] * v0[2] + v0[3] * v0[3]) + (v1[0] * v1[0] + v1[1] * v1[1]) + (v1[2] * v1[2] + v1[3] * v1[3]); }
;                 }
	v_lshlrev_b32_e32 v148, 16, v204
	v_and_b32_e32 v149, 0xffff0000, v204
	v_lshlrev_b32_e32 v182, 16, v205
	v_and_b32_e32 v183, 0xffff0000, v205
	v_lshlrev_b32_e32 v220, 16, v206
	v_and_b32_e32 v221, 0xffff0000, v206
	v_lshlrev_b32_e32 v222, 16, v207
	v_and_b32_e32 v223, 0xffff0000, v207
	v_pk_add_f32 v[94:95], v[94:95], v[148:149]
	v_pk_add_f32 v[96:97], v[96:97], v[182:183]
	v_pk_add_f32 v[90:91], v[90:91], v[220:221]
	v_pk_add_f32 v[92:93], v[92:93], v[222:223]
	v_mul_f32_e32 v168, v94, v94
	v_fmac_f32_e32 v168, v95, v95
	v_fmac_f32_e32 v168, v96, v96
	v_fmac_f32_e32 v168, v97, v97
	v_fmac_f32_e32 v168, v90, v90
	v_fmac_f32_e32 v168, v91, v91
	v_fmac_f32_e32 v168, v92, v92
	v_fmac_f32_e32 v168, v93, v93
	v_cvt_pk_bf16_f32 v204, v94, v95
	v_cvt_pk_bf16_f32 v205, v96, v97
	v_cvt_pk_bf16_f32 v206, v90, v91
	v_cvt_pk_bf16_f32 v207, v92, v93
	global_store_dwordx4 v160, v[204:207], s[30:31]
	v_lshlrev_b32_e32 v148, 16, v208
	v_and_b32_e32 v149, 0xffff0000, v208
	v_lshlrev_b32_e32 v182, 16, v209
	v_and_b32_e32 v183, 0xffff0000, v209
	v_lshlrev_b32_e32 v220, 16, v210
	v_and_b32_e32 v221, 0xffff0000, v210
	v_lshlrev_b32_e32 v222, 16, v211
	v_and_b32_e32 v223, 0xffff0000, v211
	v_pk_add_f32 v[86:87], v[86:87], v[148:149]
	v_pk_add_f32 v[88:89], v[88:89], v[182:183]
	v_pk_add_f32 v[82:83], v[82:83], v[220:221]
	v_pk_add_f32 v[84:85], v[84:85], v[222:223]
	v_fmac_f32_e32 v168, v86, v86
	v_fmac_f32_e32 v168, v87, v87
	v_fmac_f32_e32 v168, v88, v88
	v_fmac_f32_e32 v168, v89, v89
	v_fmac_f32_e32 v168, v82, v82
	v_fmac_f32_e32 v168, v83, v83
	v_fmac_f32_e32 v168, v84, v84
	v_fmac_f32_e32 v168, v85, v85
	v_cvt_pk_bf16_f32 v208, v86, v87
	v_cvt_pk_bf16_f32 v209, v88, v89
	v_cvt_pk_bf16_f32 v210, v82, v83
	v_cvt_pk_bf16_f32 v211, v84, v85
	global_store_dwordx4 v160, v[208:211], s[30:31] offset:256
	s_waitcnt vmcnt(6)
	v_lshlrev_b32_e32 v148, 16, v212
	v_and_b32_e32 v149, 0xffff0000, v212
	v_lshlrev_b32_e32 v182, 16, v213
	v_and_b32_e32 v183, 0xffff0000, v213
	v_lshlrev_b32_e32 v220, 16, v214
	v_and_b32_e32 v221, 0xffff0000, v214
	v_lshlrev_b32_e32 v222, 16, v215
	v_and_b32_e32 v223, 0xffff0000, v215
	v_pk_add_f32 v[78:79], v[78:79], v[148:149]
	v_pk_add_f32 v[80:81], v[80:81], v[182:183]
	v_pk_add_f32 v[74:75], v[74:75], v[220:221]
	v_pk_add_f32 v[76:77], v[76:77], v[222:223]
	v_mul_f32_e32 v169, v78, v78
	v_fmac_f32_e32 v169, v79, v79
	v_fmac_f32_e32 v169, v80, v80
	v_fmac_f32_e32 v169, v81, v81
	v_fmac_f32_e32 v169, v74, v74
	v_fmac_f32_e32 v169, v75, v75
	v_fmac_f32_e32 v169, v76, v76
	v_fmac_f32_e32 v169, v77, v77
	v_cvt_pk_bf16_f32 v212, v78, v79
	v_cvt_pk_bf16_f32 v213, v80, v81
	v_cvt_pk_bf16_f32 v214, v74, v75
	v_cvt_pk_bf16_f32 v215, v76, v77
	global_store_dwordx4 v161, v[212:215], s[30:31]
	v_lshlrev_b32_e32 v148, 16, v216
	v_and_b32_e32 v149, 0xffff0000, v216
	v_lshlrev_b32_e32 v182, 16, v217
	v_and_b32_e32 v183, 0xffff0000, v217
	v_lshlrev_b32_e32 v220, 16, v218
	v_and_b32_e32 v221, 0xffff0000, v218
	v_lshlrev_b32_e32 v222, 16, v219
	v_and_b32_e32 v223, 0xffff0000, v219
	v_pk_add_f32 v[70:71], v[70:71], v[148:149]
	v_pk_add_f32 v[72:73], v[72:73], v[182:183]
	v_pk_add_f32 v[66:67], v[66:67], v[220:221]
	v_pk_add_f32 v[68:69], v[68:69], v[222:223]
	v_fmac_f32_e32 v169, v70, v70
	v_fmac_f32_e32 v169, v71, v71
	v_fmac_f32_e32 v169, v72, v72
	v_fmac_f32_e32 v169, v73, v73
	v_fmac_f32_e32 v169, v66, v66
	v_fmac_f32_e32 v169, v67, v67
	v_fmac_f32_e32 v169, v68, v68
	v_fmac_f32_e32 v169, v69, v69
	v_cvt_pk_bf16_f32 v216, v70, v71
	v_cvt_pk_bf16_f32 v217, v72, v73
	v_cvt_pk_bf16_f32 v218, v66, v67
	v_cvt_pk_bf16_f32 v219, v68, v69
	global_store_dwordx4 v161, v[216:219], s[30:31] offset:256
	global_load_dwordx4 v[188:191], v162, s[30:31]
	global_load_dwordx4 v[192:195], v162, s[30:31] offset:256
	global_load_dwordx4 v[196:199], v163, s[30:31]
	global_load_dwordx4 v[200:203], v163, s[30:31] offset:256
	global_load_dwordx4 v[204:207], v164, s[30:31]
	global_load_dwordx4 v[208:211], v164, s[30:31] offset:256
	global_load_dwordx4 v[212:215], v165, s[30:31]
	global_load_dwordx4 v[216:219], v165, s[30:31] offset:256
	s_waitcnt vmcnt(6)
	v_lshlrev_b32_e32 v148, 16, v188
	v_and_b32_e32 v149, 0xffff0000, v188
	v_lshlrev_b32_e32 v182, 16, v189
	v_and_b32_e32 v183, 0xffff0000, v189
	v_lshlrev_b32_e32 v220, 16, v190
	v_and_b32_e32 v221, 0xffff0000, v190
	v_lshlrev_b32_e32 v222, 16, v191
	v_and_b32_e32 v223, 0xffff0000, v191
	v_pk_add_f32 v[62:63], v[62:63], v[148:149]
	v_pk_add_f32 v[64:65], v[64:65], v[182:183]
	v_pk_add_f32 v[58:59], v[58:59], v[220:221]
	v_pk_add_f32 v[60:61], v[60:61], v[222:223]
	v_mul_f32_e32 v170, v62, v62
	v_fmac_f32_e32 v170, v63, v63
	v_fmac_f32_e32 v170, v64, v64
	v_fmac_f32_e32 v170, v65, v65
	v_fmac_f32_e32 v170, v58, v58
	v_fmac_f32_e32 v170, v59, v59
	v_fmac_f32_e32 v170, v60, v60
	v_fmac_f32_e32 v170, v61, v61
	v_cvt_pk_bf16_f32 v188, v62, v63
	v_cvt_pk_bf16_f32 v189, v64, v65
	v_cvt_pk_bf16_f32 v190, v58, v59
	v_cvt_pk_bf16_f32 v191, v60, v61
	global_store_dwordx4 v162, v[188:191], s[30:31]
	v_lshlrev_b32_e32 v148, 16, v192
	v_and_b32_e32 v149, 0xffff0000, v192
	v_lshlrev_b32_e32 v182, 16, v193
	v_and_b32_e32 v183, 0xffff0000, v193
	v_lshlrev_b32_e32 v220, 16, v194
	v_and_b32_e32 v221, 0xffff0000, v194
	v_lshlrev_b32_e32 v222, 16, v195
	v_and_b32_e32 v223, 0xffff0000, v195
	v_pk_add_f32 v[54:55], v[54:55], v[148:149]
	v_pk_add_f32 v[56:57], v[56:57], v[182:183]
	v_pk_add_f32 v[50:51], v[50:51], v[220:221]
	v_pk_add_f32 v[52:53], v[52:53], v[222:223]
	v_fmac_f32_e32 v170, v54, v54
	v_fmac_f32_e32 v170, v55, v55
	v_fmac_f32_e32 v170, v56, v56
	v_fmac_f32_e32 v170, v57, v57
	v_fmac_f32_e32 v170, v50, v50
	v_fmac_f32_e32 v170, v51, v51
	v_fmac_f32_e32 v170, v52, v52
	v_fmac_f32_e32 v170, v53, v53
	v_cvt_pk_bf16_f32 v192, v54, v55
	v_cvt_pk_bf16_f32 v193, v56, v57
	v_cvt_pk_bf16_f32 v194, v50, v51
	v_cvt_pk_bf16_f32 v195, v52, v53
	global_store_dwordx4 v162, v[192:195], s[30:31] offset:256
	s_waitcnt vmcnt(6)
; DI float bf_lo(unsigned u) { return __uint_as_float(u << 16); }
; DI float bf_hi(unsigned u) { return __uint_as_float(u & 0xffff0000u); }
;     DI void operator()(Acc& acc, const pg8::Unit& u, int wr, int wc, int fr, int fq, const Pre&) const {
;     ...
;             for (int m = 0; m < 4; ++m) {
;                 const int row = u.pm * 256 + ai * 128 + wr * 64 + m * 16 + fr;
;                 float ss = 0.f;
; #pragma unroll
;                 for (int bj = 0; bj < 2; ++bj) {
;                     const size_t off = (size_t)row * DM + col + bj * 128;
;                     f32x4 r0, r1;
;                     if (RES_BF16) { const u32x4 rb = *(const u32x4*)(xb + off); r0 = (f32x4){bf_lo(rb.x), bf_hi(rb.x), bf_lo(rb.y), bf_hi(rb.y)}; r1 = (f32x4){bf_lo(rb.z), bf_hi(rb.z), bf_lo(rb.w), bf_hi(rb.w)}; }
;                     else { r0 = *(const f32x4*)(res + off); r1 = *(const f32x4*)(res + off + 4); }
;                     const f32x4 v0 = r0 + acc[ai][bj][m][0] * coef, v1 = r1 + acc[ai][bj][m][1] * coef;
;                     if (WRITE_F32) { *(f32x4*)(out + off) = v0; *(f32x4*)(out + off + 4) = v1; }
;                     if (WRITE_XB) { store8(xb + off, v0, v1);
;                         ss += (v0[0] * v0[0] + v0[1] * v0[1]) + (v0[2] * v0[2] + v0[3] * v0[3]) + (v1[0] * v1[0] + v1[1] * v1[1]) + (v1[2] * v1[2] + v1[3] * v1[3]); }
;                 }
;                 if (WRITE_XB) { ss += __shfl_xor(ss, 16); ss += __shfl_xor(ss, 32); if (fq == 0) __hip_atomic_fetch_add(ssq + row, ss, __ATOMIC_RELAXED, __HIP_MEMORY_SCOPE_AGENT); }
	v_lshlrev_b32_e32 v148, 16, v196
	v_and_b32_e32 v149, 0xffff0000, v196
	v_lshlrev_b32_e32 v182, 16, v197
	v_and_b32_e32 v183, 0xffff0000, v197
	v_lshlrev_b32_e32 v220, 16, v198
	v_and_b32_e32 v221, 0xffff0000, v198
	v_lshlrev_b32_e32 v222, 16, v199
	v_and_b32_e32 v223, 0xffff0000, v199
	v_pk_add_f32 v[46:47], v[46:47], v[148:149]
	v_pk_add_f32 v[48:49], v[48:49], v[182:183]
	v_pk_add_f32 v[42:43], v[42:43], v[220:221]
	v_pk_add_f32 v[44:45], v[44:45], v[222:223]
	v_mul_f32_e32 v171, v46, v46
	v_fmac_f32_e32 v171, v47, v47
	v_fmac_f32_e32 v171, v48, v48
	v_fmac_f32_e32 v171, v49, v49
	v_fmac_f32_e32 v171, v42, v42
	v_fmac_f32_e32 v171, v43, v43
	v_fmac_f32_e32 v171, v44, v44
	v_fmac_f32_e32 v171, v45, v45
	v_cvt_pk_bf16_f32 v196, v46, v47
	v_cvt_pk_bf16_f32 v197, v48, v49
	v_cvt_pk_bf16_f32 v198, v42, v43
	v_cvt_pk_bf16_f32 v199, v44, v45
	global_store_dwordx4 v163, v[196:199], s[30:31]
	v_lshlrev_b32_e32 v148, 16, v200
	v_and_b32_e32 v149, 0xffff0000, v200
	v_lshlrev_b32_e32 v182, 16, v201
	v_and_b32_e32 v183, 0xffff0000, v201
	v_lshlrev_b32_e32 v220, 16, v202
	v_and_b32_e32 v221, 0xffff0000, v202
	v_lshlrev_b32_e32 v222, 16, v203
	v_and_b32_e32 v223, 0xffff0000, v203
	v_pk_add_f32 v[38:39], v[38:39], v[148:149]
	v_pk_add_f32 v[40:41], v[40:41], v[182:183]
	v_pk_add_f32 v[34:35], v[34:35], v[220:221]
	v_pk_add_f32 v[36:37], v[36:37], v[222:223]
	v_fmac_f32_e32 v171, v38, v38
	v_fmac_f32_e32 v171, v39, v39
	v_fmac_f32_e32 v171, v40, v40
	v_fmac_f32_e32 v171, v41, v41
	v_fmac_f32_e32 v171, v34, v34
	v_fmac_f32_e32 v171, v35, v35
	v_fmac_f32_e32 v171, v36, v36
	v_fmac_f32_e32 v171, v37, v37
	v_cvt_pk_bf16_f32 v200, v38, v39
	v_cvt_pk_bf16_f32 v201, v40, v41
	v_cvt_pk_bf16_f32 v202, v34, v35
	v_cvt_pk_bf16_f32 v203, v36, v37
	global_store_dwordx4 v163, v[200:203], s[30:31] offset:256
	s_waitcnt vmcnt(6)
	v_lshlrev_b32_e32 v148, 16, v204
	v_and_b32_e32 v149, 0xffff0000, v204
	v_lshlrev_b32_e32 v182, 16, v205
	v_and_b32_e32 v183, 0xffff0000, v205
	v_lshlrev_b32_e32 v220, 16, v206
	v_and_b32_e32 v221, 0xffff0000, v206
	v_lshlrev_b32_e32 v222, 16, v207
	v_and_b32_e32 v223, 0xffff0000, v207
	v_pk_add_f32 v[30:31], v[30:31], v[148:149]
	v_pk_add_f32 v[32:33], v[32:33], v[182:183]
	v_pk_add_f32 v[26:27], v[26:27], v[220:221]
	v_pk_add_f32 v[28:29], v[28:29], v[222:223]
	v_mul_f32_e32 v172, v30, v30
	v_fmac_f32_e32 v172, v31, v31
	v_fmac_f32_e32 v172, v32, v32
	v_fmac_f32_e32 v172, v33, v33
	v_fmac_f32_e32 v172, v26, v26
	v_fmac_f32_e32 v172, v27, v27
	v_fmac_f32_e32 v172, v28, v28
	v_fmac_f32_e32 v172, v29, v29
	v_cvt_pk_bf16_f32 v204, v30, v31
	v_cvt_pk_bf16_f32 v205, v32, v33
	v_cvt_pk_bf16_f32 v206, v26, v27
	v_cvt_pk_bf16_f32 v207, v28, v29
	global_store_dwordx4 v164, v[204:207], s[30:31]
	v_lshlrev_b32_e32 v148, 16, v208
	v_and_b32_e32 v149, 0xffff0000, v208
	v_lshlrev_b32_e32 v182, 16, v209
	v_and_b32_e32 v183, 0xffff0000, v209
	v_lshlrev_b32_e32 v220, 16, v210
	v_and_b32_e32 v221, 0xffff0000, v210
	v_lshlrev_b32_e32 v222, 16, v211
	v_and_b32_e32 v223, 0xffff0000, v211
	v_pk_add_f32 v[22:23], v[22:23], v[148:149]
	v_pk_add_f32 v[24:25], v[24:25], v[182:183]
	v_pk_add_f32 v[18:19], v[18:19], v[220:221]
	v_pk_add_f32 v[20:21], v[20:21], v[222:223]
	v_fmac_f32_e32 v172, v22, v22
	v_fmac_f32_e32 v172, v23, v23
	v_fmac_f32_e32 v172, v24, v24
	v_fmac_f32_e32 v172, v25, v25
	v_fmac_f32_e32 v172, v18, v18
	v_fmac_f32_e32 v172, v19, v19
	v_fmac_f32_e32 v172, v20, v20
	v_fmac_f32_e32 v172, v21, v21
	v_cvt_pk_bf16_f32 v208, v22, v23
	v_cvt_pk_bf16_f32 v209, v24, v25
	v_cvt_pk_bf16_f32 v210, v18, v19
	v_cvt_pk_bf16_f32 v211, v20, v21
	global_store_dwordx4 v164, v[208:211], s[30:31] offset:256
	s_waitcnt vmcnt(6)
	v_lshlrev_b32_e32 v148, 16, v212
	v_and_b32_e32 v149, 0xffff0000, v212
	v_lshlrev_b32_e32 v182, 16, v213
	v_and_b32_e32 v183, 0xffff0000, v213
	v_lshlrev_b32_e32 v220, 16, v214
	v_and_b32_e32 v221, 0xffff0000, v214
	v_lshlrev_b32_e32 v222, 16, v215
	v_and_b32_e32 v223, 0xffff0000, v215
	v_pk_add_f32 v[14:15], v[14:15], v[148:149]
	v_pk_add_f32 v[16:17], v[16:17], v[182:183]
	v_pk_add_f32 v[10:11], v[10:11], v[220:221]
	v_pk_add_f32 v[12:13], v[12:13], v[222:223]
	v_mul_f32_e32 v173, v14, v14
	v_fmac_f32_e32 v173, v15, v15
	v_fmac_f32_e32 v173, v16, v16
	v_fmac_f32_e32 v173, v17, v17
	v_fmac_f32_e32 v173, v10, v10
	v_fmac_f32_e32 v173, v11, v11
	v_fmac_f32_e32 v173, v12, v12
	v_fmac_f32_e32 v173, v13, v13
	v_cvt_pk_bf16_f32 v212, v14, v15
	v_cvt_pk_bf16_f32 v213, v16, v17
	v_cvt_pk_bf16_f32 v214, v10, v11
	v_cvt_pk_bf16_f32 v215, v12, v13
	global_store_dwordx4 v165, v[212:215], s[30:31]
	v_lshlrev_b32_e32 v148, 16, v216
	v_and_b32_e32 v149, 0xffff0000, v216
	v_lshlrev_b32_e32 v182, 16, v217
	v_and_b32_e32 v183, 0xffff0000, v217
	v_lshlrev_b32_e32 v220, 16, v218
	v_and_b32_e32 v221, 0xffff0000, v218
	v_lshlrev_b32_e32 v222, 16, v219
	v_and_b32_e32 v223, 0xffff0000, v219
	v_pk_add_f32 v[6:7], v[6:7], v[148:149]
	v_pk_add_f32 v[8:9], v[8:9], v[182:183]
	v_pk_add_f32 v[2:3], v[2:3], v[220:221]
	v_pk_add_f32 v[4:5], v[4:5], v[222:223]
	v_fmac_f32_e32 v173, v6, v6
	v_fmac_f32_e32 v173, v7, v7
	v_fmac_f32_e32 v173, v8, v8
	v_fmac_f32_e32 v173, v9, v9
	v_fmac_f32_e32 v173, v2, v2
	v_fmac_f32_e32 v173, v3, v3
	v_fmac_f32_e32 v173, v4, v4
	v_fmac_f32_e32 v173, v5, v5
	v_cvt_pk_bf16_f32 v216, v6, v7
	v_cvt_pk_bf16_f32 v217, v8, v9
	v_cvt_pk_bf16_f32 v218, v2, v3
	v_cvt_pk_bf16_f32 v219, v4, v5
	global_store_dwordx4 v165, v[216:219], s[30:31] offset:256
	ds_bpermute_b32 v174, v226, v166
	ds_bpermute_b32 v175, v226, v167
	ds_bpermute_b32 v176, v226, v168
	ds_bpermute_b32 v177, v226, v169
	ds_bpermute_b32 v178, v226, v170
	ds_bpermute_b32 v179, v226, v171
	ds_bpermute_b32 v180, v226, v172
	ds_bpermute_b32 v181, v226, v173
	s_waitcnt lgkmcnt(0)
	v_add_f32_e32 v166, v166, v174
	v_add_f32_e32 v167, v167, v175
	v_add_f32_e32 v168, v168, v176
	v_add_f32_e32 v169, v169, v177
	v_add_f32_e32 v170, v170, v178
	v_add_f32_e32 v171, v171, v179
	v_add_f32_e32 v172, v172, v180
	v_add_f32_e32 v173, v173, v181
	ds_bpermute_b32 v174, v227, v166
	ds_bpermute_b32 v175, v227, v167
	ds_bpermute_b32 v176, v227, v168
	ds_bpermute_b32 v177, v227, v169
	ds_bpermute_b32 v178, v227, v170
	ds_bpermute_b32 v179, v227, v171
	ds_bpermute_b32 v180, v227, v172
	ds_bpermute_b32 v181, v227, v173
	s_waitcnt lgkmcnt(0)
	v_add_f32_e32 v166, v166, v174
	v_add_f32_e32 v167, v167, v175
	v_add_f32_e32 v168, v168, v176
	v_add_f32_e32 v169, v169, v177
	v_add_f32_e32 v170, v170, v178
	v_add_f32_e32 v171, v171, v179
	v_add_f32_e32 v172, v172, v180
	v_add_f32_e32 v173, v173, v181
	v_lshlrev_b32_e32 v224, 2, v224
	s_and_saveexec_b64 s[40:41], s[4:5]
	global_atomic_add_f32 v224, v166, s[8:9]
	global_atomic_add_f32 v224, v167, s[8:9] offset:64
	global_atomic_add_f32 v224, v168, s[8:9] offset:128
	global_atomic_add_f32 v224, v169, s[8:9] offset:192
	global_atomic_add_f32 v224, v170, s[8:9] offset:512
	global_atomic_add_f32 v224, v171, s[8:9] offset:576
	global_atomic_add_f32 v224, v172, s[8:9] offset:640
	global_atomic_add_f32 v224, v173, s[8:9] offset:704
